# v24 + per-unit GEMM accumulator zeroing with v_mov_b64 (64 instead of 127 moves)
# speedup vs baseline: 1.0019x; 1.0001x over previous
; template <class Epi, class Sched, bool ALIGN_EPI = false, bool SP2 = false>
; __device__ __forceinline__ void gemm_phase(PG8_LAS unsigned char* lds, const Gemm g, const Sched& S, const Epi& E) {
;     ...
; #pragma unroll
;         for (int a = 0; a < 2; ++a)
; #pragma unroll
;             for (int b = 0; b < 2; ++b)
; #pragma unroll
;                 for (int m = 0; m < 4; ++m)
; #pragma unroll
;                     for (int n = 0; n < 2; ++n) acc[a][b][m][n] = (f32x4){0.f, 0.f, 0.f, 0.f};
;         cur = nxt; cA = nA; cB = nB; ++ui;
.LBB0_379:
	s_add_u32 s77, s78, 0x100
	s_addc_u32 s83, s79, 0
	s_add_u32 s78, s84, 0x80
	v_mov_b32_e32 v0, 0
	s_addc_u32 s79, s85, 0
	s_mov_b32 s40, 0
	v_mov_b32_e32 v1, 0
	v_mov_b64_e32 v[2:3], v[0:1]
	v_mov_b64_e32 v[4:5], v[0:1]
	v_mov_b64_e32 v[6:7], v[0:1]
	v_mov_b64_e32 v[8:9], v[0:1]
	v_mov_b64_e32 v[10:11], v[0:1]
	v_mov_b64_e32 v[12:13], v[0:1]
	v_mov_b64_e32 v[14:15], v[0:1]
	v_mov_b64_e32 v[16:17], v[0:1]
	v_mov_b64_e32 v[18:19], v[0:1]
	v_mov_b64_e32 v[20:21], v[0:1]
	v_mov_b64_e32 v[22:23], v[0:1]
	v_mov_b64_e32 v[24:25], v[0:1]
	v_mov_b64_e32 v[26:27], v[0:1]
	v_mov_b64_e32 v[28:29], v[0:1]
	v_mov_b64_e32 v[30:31], v[0:1]
	v_mov_b64_e32 v[32:33], v[0:1]
	v_mov_b64_e32 v[34:35], v[0:1]
	v_mov_b64_e32 v[36:37], v[0:1]
	v_mov_b64_e32 v[38:39], v[0:1]
	v_mov_b64_e32 v[40:41], v[0:1]
	v_mov_b64_e32 v[42:43], v[0:1]
	v_mov_b64_e32 v[44:45], v[0:1]
	v_mov_b64_e32 v[46:47], v[0:1]
	v_mov_b64_e32 v[48:49], v[0:1]
	v_mov_b64_e32 v[50:51], v[0:1]
	v_mov_b64_e32 v[52:53], v[0:1]
	v_mov_b64_e32 v[54:55], v[0:1]
	v_mov_b64_e32 v[56:57], v[0:1]
	v_mov_b64_e32 v[58:59], v[0:1]
	v_mov_b64_e32 v[60:61], v[0:1]
	v_mov_b64_e32 v[62:63], v[0:1]
	v_mov_b64_e32 v[64:65], v[0:1]
	v_mov_b64_e32 v[66:67], v[0:1]
	v_mov_b64_e32 v[68:69], v[0:1]
	v_mov_b64_e32 v[70:71], v[0:1]
	v_mov_b64_e32 v[72:73], v[0:1]
	v_mov_b64_e32 v[74:75], v[0:1]
	v_mov_b64_e32 v[76:77], v[0:1]
	v_mov_b64_e32 v[78:79], v[0:1]
	v_mov_b64_e32 v[80:81], v[0:1]
	v_mov_b64_e32 v[82:83], v[0:1]
	v_mov_b64_e32 v[84:85], v[0:1]
	v_mov_b64_e32 v[86:87], v[0:1]
	v_mov_b64_e32 v[88:89], v[0:1]
	v_mov_b64_e32 v[90:91], v[0:1]
	v_mov_b64_e32 v[92:93], v[0:1]
	v_mov_b64_e32 v[94:95], v[0:1]
	v_mov_b64_e32 v[96:97], v[0:1]
	v_mov_b64_e32 v[98:99], v[0:1]
	v_mov_b64_e32 v[100:101], v[0:1]
	v_mov_b64_e32 v[102:103], v[0:1]
	v_mov_b64_e32 v[104:105], v[0:1]
	v_mov_b64_e32 v[106:107], v[0:1]
	v_mov_b64_e32 v[108:109], v[0:1]
	v_mov_b64_e32 v[110:111], v[0:1]
	v_mov_b64_e32 v[112:113], v[0:1]
	v_mov_b64_e32 v[114:115], v[0:1]
	v_mov_b64_e32 v[116:117], v[0:1]
	v_mov_b64_e32 v[118:119], v[0:1]
	v_mov_b64_e32 v[120:121], v[0:1]
	v_mov_b64_e32 v[122:123], v[0:1]
	v_mov_b64_e32 v[136:137], v[0:1]
	v_mov_b64_e32 v[138:139], v[0:1]

; template <class Epi, class Sched, bool ALIGN_EPI = false, bool SP2 = false>
; __device__ __forceinline__ void gemm_phase(PG8_LAS unsigned char* lds, const Gemm g, const Sched& S, const Epi& E) {
;     ...
; #pragma unroll
;         for (int a = 0; a < 2; ++a)
; #pragma unroll
;             for (int b = 0; b < 2; ++b)
; #pragma unroll
;                 for (int m = 0; m < 4; ++m)
; #pragma unroll
;                     for (int n = 0; n < 2; ++n) acc[a][b][m][n] = (f32x4){0.f, 0.f, 0.f, 0.f};
;         cur = nxt; cA = nA; cB = nB; ++ui;
.LBB0_425:
	s_add_u32 s83, s92, 0x100
	s_addc_u32 s88, s93, 0
	s_add_u32 s44, s40, 0x80
	v_mov_b32_e32 v0, 0
	s_addc_u32 s45, s41, 0
	s_mov_b32 s40, 0
	v_mov_b32_e32 v1, 0
	v_mov_b64_e32 v[2:3], v[0:1]
	v_mov_b64_e32 v[4:5], v[0:1]
	v_mov_b64_e32 v[6:7], v[0:1]
	v_mov_b64_e32 v[8:9], v[0:1]
	v_mov_b64_e32 v[10:11], v[0:1]
	v_mov_b64_e32 v[12:13], v[0:1]
	v_mov_b64_e32 v[14:15], v[0:1]
	v_mov_b64_e32 v[16:17], v[0:1]
	v_mov_b64_e32 v[18:19], v[0:1]
	v_mov_b64_e32 v[20:21], v[0:1]
	v_mov_b64_e32 v[22:23], v[0:1]
	v_mov_b64_e32 v[24:25], v[0:1]
	v_mov_b64_e32 v[26:27], v[0:1]
	v_mov_b64_e32 v[28:29], v[0:1]
	v_mov_b64_e32 v[30:31], v[0:1]
	v_mov_b64_e32 v[32:33], v[0:1]
	v_mov_b64_e32 v[34:35], v[0:1]
	v_mov_b64_e32 v[36:37], v[0:1]
	v_mov_b64_e32 v[38:39], v[0:1]
	v_mov_b64_e32 v[40:41], v[0:1]
	v_mov_b64_e32 v[42:43], v[0:1]
	v_mov_b64_e32 v[44:45], v[0:1]
	v_mov_b64_e32 v[46:47], v[0:1]
	v_mov_b64_e32 v[48:49], v[0:1]
	v_mov_b64_e32 v[50:51], v[0:1]
	v_mov_b64_e32 v[52:53], v[0:1]
	v_mov_b64_e32 v[54:55], v[0:1]
	v_mov_b64_e32 v[56:57], v[0:1]
	v_mov_b64_e32 v[58:59], v[0:1]
	v_mov_b64_e32 v[60:61], v[0:1]
	v_mov_b64_e32 v[62:63], v[0:1]
	v_mov_b64_e32 v[64:65], v[0:1]
	v_mov_b64_e32 v[66:67], v[0:1]
	v_mov_b64_e32 v[68:69], v[0:1]
	v_mov_b64_e32 v[70:71], v[0:1]
	v_mov_b64_e32 v[72:73], v[0:1]
	v_mov_b64_e32 v[74:75], v[0:1]
	v_mov_b64_e32 v[76:77], v[0:1]
	v_mov_b64_e32 v[78:79], v[0:1]
	v_mov_b64_e32 v[80:81], v[0:1]
	v_mov_b64_e32 v[82:83], v[0:1]
	v_mov_b64_e32 v[84:85], v[0:1]
	v_mov_b64_e32 v[86:87], v[0:1]
	v_mov_b64_e32 v[88:89], v[0:1]
	v_mov_b64_e32 v[90:91], v[0:1]
	v_mov_b64_e32 v[92:93], v[0:1]
	v_mov_b64_e32 v[94:95], v[0:1]
	v_mov_b64_e32 v[96:97], v[0:1]
	v_mov_b64_e32 v[98:99], v[0:1]
	v_mov_b64_e32 v[100:101], v[0:1]
	v_mov_b64_e32 v[102:103], v[0:1]
	v_mov_b64_e32 v[104:105], v[0:1]
	v_mov_b64_e32 v[106:107], v[0:1]
	v_mov_b64_e32 v[108:109], v[0:1]
	v_mov_b64_e32 v[110:111], v[0:1]
	v_mov_b64_e32 v[112:113], v[0:1]
	v_mov_b64_e32 v[114:115], v[0:1]
	v_mov_b64_e32 v[116:117], v[0:1]
	v_mov_b64_e32 v[118:119], v[0:1]
	v_mov_b64_e32 v[120:121], v[0:1]
	v_mov_b64_e32 v[122:123], v[0:1]
	v_mov_b64_e32 v[124:125], v[0:1]
	v_mov_b64_e32 v[126:127], v[0:1]

; template <class Epi, class Sched, bool ALIGN_EPI = false, bool SP2 = false>
; __device__ __forceinline__ void gemm_phase(PG8_LAS unsigned char* lds, const Gemm g, const Sched& S, const Epi& E) {
;     ...
; #pragma unroll
;         for (int a = 0; a < 2; ++a)
; #pragma unroll
;             for (int b = 0; b < 2; ++b)
; #pragma unroll
;                 for (int m = 0; m < 4; ++m)
; #pragma unroll
;                     for (int n = 0; n < 2; ++n) acc[a][b][m][n] = (f32x4){0.f, 0.f, 0.f, 0.f};
;         cur = nxt; cA = nA; cB = nB; ++ui;
.LBB0_459:
	s_add_u32 vcc_lo, s40, 0x100
	s_addc_u32 vcc_hi, s41, 0
	s_add_u32 s44, s76, 0x80
	v_mov_b32_e32 v0, 0
	s_addc_u32 s45, s77, 0
	s_mov_b32 s40, 0
	s_waitcnt lgkmcnt(0)
	v_mov_b32_e32 v1, 0
	v_mov_b64_e32 v[2:3], v[0:1]
	v_mov_b64_e32 v[4:5], v[0:1]
	v_mov_b64_e32 v[6:7], v[0:1]
	v_mov_b64_e32 v[8:9], v[0:1]
	v_mov_b64_e32 v[10:11], v[0:1]
	v_mov_b64_e32 v[12:13], v[0:1]
	v_mov_b64_e32 v[14:15], v[0:1]
	v_mov_b64_e32 v[16:17], v[0:1]
	v_mov_b64_e32 v[18:19], v[0:1]
	v_mov_b64_e32 v[20:21], v[0:1]
	v_mov_b64_e32 v[22:23], v[0:1]
	v_mov_b64_e32 v[24:25], v[0:1]
	v_mov_b64_e32 v[26:27], v[0:1]
	v_mov_b64_e32 v[28:29], v[0:1]
	v_mov_b64_e32 v[30:31], v[0:1]
	v_mov_b64_e32 v[32:33], v[0:1]
	v_mov_b64_e32 v[34:35], v[0:1]
	v_mov_b64_e32 v[36:37], v[0:1]
	v_mov_b64_e32 v[38:39], v[0:1]
	v_mov_b64_e32 v[40:41], v[0:1]
	v_mov_b64_e32 v[42:43], v[0:1]
	v_mov_b64_e32 v[44:45], v[0:1]
	v_mov_b64_e32 v[46:47], v[0:1]
	v_mov_b64_e32 v[48:49], v[0:1]
	v_mov_b64_e32 v[50:51], v[0:1]
	v_mov_b64_e32 v[52:53], v[0:1]
	v_mov_b64_e32 v[54:55], v[0:1]
	v_mov_b64_e32 v[56:57], v[0:1]
	v_mov_b64_e32 v[58:59], v[0:1]
	v_mov_b64_e32 v[60:61], v[0:1]
	v_mov_b64_e32 v[62:63], v[0:1]
	v_mov_b64_e32 v[64:65], v[0:1]
	v_mov_b64_e32 v[66:67], v[0:1]
	v_mov_b64_e32 v[68:69], v[0:1]
	v_mov_b64_e32 v[70:71], v[0:1]
	v_mov_b64_e32 v[72:73], v[0:1]
	v_mov_b64_e32 v[74:75], v[0:1]
	v_mov_b64_e32 v[76:77], v[0:1]
	v_mov_b64_e32 v[78:79], v[0:1]
	v_mov_b64_e32 v[80:81], v[0:1]
	v_mov_b64_e32 v[82:83], v[0:1]
	v_mov_b64_e32 v[84:85], v[0:1]
	v_mov_b64_e32 v[86:87], v[0:1]
	v_mov_b64_e32 v[88:89], v[0:1]
	v_mov_b64_e32 v[90:91], v[0:1]
	v_mov_b64_e32 v[92:93], v[0:1]
	v_mov_b64_e32 v[94:95], v[0:1]
	v_mov_b64_e32 v[96:97], v[0:1]
	v_mov_b64_e32 v[98:99], v[0:1]
	v_mov_b64_e32 v[100:101], v[0:1]
	v_mov_b64_e32 v[102:103], v[0:1]
	v_mov_b64_e32 v[104:105], v[0:1]
	v_mov_b64_e32 v[106:107], v[0:1]
	v_mov_b64_e32 v[108:109], v[0:1]
	v_mov_b64_e32 v[110:111], v[0:1]
	v_mov_b64_e32 v[112:113], v[0:1]
	v_mov_b64_e32 v[114:115], v[0:1]
	v_mov_b64_e32 v[116:117], v[0:1]
	v_mov_b64_e32 v[118:119], v[0:1]
	v_mov_b64_e32 v[120:121], v[0:1]
	v_mov_b64_e32 v[122:123], v[0:1]
	v_mov_b64_e32 v[124:125], v[0:1]
	v_mov_b64_e32 v[126:127], v[0:1]
